# adds: P6 normalisation with the 16 row-sum reductions interleaved (8 ds_bpermute chains per step)
# baseline (speedup 1.0000x reference)
; __device__ __forceinline__ void lds_add(LAS float* p, float v) { __hip_atomic_fetch_add(p, v, __ATOMIC_RELAXED, __HIP_MEMORY_SCOPE_WORKGROUP); }
; __device__ __forceinline__ void mlstm_out_unit(const Frame& F, int c, int h, int tb) {
;     ...
; #pragma unroll
;     for (int tt = 0; tt < 4; ++tt)
; #pragma unroll
;         for (int j = 0; j < 4; ++j) { const int tl = tt * 16 + kg * 4 + j; const float mt = BC[t0 + tl] + sMr[tl]; const float dn = 1.f / fmaxf(fabsf(sDen[tl]), expf(-mt));
;             acc[tt][0][j] *= dn; acc[tt][1][j] *= dn; float q = acc[tt][0][j] * acc[tt][0][j] + acc[tt][1][j] * acc[tt][1][j];
;             q += __shfl_xor(q, 1); q += __shfl_xor(q, 2); q += __shfl_xor(q, 4); q += __shfl_xor(q, 8);
;             if (fr == 0) lds_add(&sSq[tl], q); }
.LBB0_775:
	s_add_u32 s16, s20, s49
	s_addc_u32 s17, s21, 0
	v_or_b32_e32 v74, s47, v106
	v_lshl_add_u64 v[24:25], v[74:75], 2, s[16:17]
	global_load_dwordx4 v[216:219], v[24:25], off
	global_load_dwordx4 v[220:223], v[24:25], off offset:64
	global_load_dwordx4 v[224:227], v[24:25], off offset:128
	global_load_dwordx4 v[228:231], v[24:25], off offset:192
	ds_read_b32 v25, v126
	ds_read_b32 v26, v127
	s_waitcnt lgkmcnt(0)
	v_max_f32_e64 v26, |v26|, |v26|
	s_waitcnt vmcnt(0)
	v_add_f32_e32 v24, v216, v25
	v_mul_f32_e32 v25, 0xbfb8aa3b, v24
	v_fma_f32 v27, v24, s42, -v25
	v_rndne_f32_e32 v28, v25
	v_fmac_f32_e32 v27, 0xb2a5705f, v24
	v_sub_f32_e32 v25, v25, v28
	v_add_f32_e32 v25, v25, v27
	v_cvt_i32_f32_e32 v28, v28
	v_exp_f32_e32 v25, v25
	v_cmp_nlt_f32_e32 vcc, s43, v24
	v_ldexp_f32 v25, v25, v28
	s_nop 0
	v_cndmask_b32_e32 v25, 0, v25, vcc
	v_cmp_ngt_f32_e32 vcc, s44, v24
	s_nop 1
	v_cndmask_b32_e32 v24, v209, v25, vcc
	v_max_f32_e32 v24, v26, v24
	v_div_scale_f32 v25, s[18:19], v24, v24, 1.0
	v_rcp_f32_e32 v26, v25
	v_div_scale_f32 v27, vcc, 1.0, v24, 1.0
	v_fma_f32 v28, -v25, v26, 1.0
	v_fmac_f32_e32 v26, v28, v26
	v_mul_f32_e32 v28, v27, v26
	v_fma_f32 v29, -v25, v28, v27
	v_fmac_f32_e32 v28, v29, v26
	v_fma_f32 v25, -v25, v28, v27
	v_div_fmas_f32 v25, v25, v26, v28
	v_div_fixup_f32 v24, v25, v24, 1.0
	v_mul_f32_e32 v32, v60, v24
	v_mul_f32_e32 v38, v56, v24
	v_mul_f32_e32 v24, v32, v32
	v_fmac_f32_e32 v24, v38, v38
	v_mov_b32_e32 v216, v24
	v_add_u32_e32 v24, s47, v106
	s_waitcnt lgkmcnt(0)
	v_mov_b32_e32 v25, v75
	v_lshl_add_u64 v[24:25], v[24:25], 2, s[16:17]
	v_mov_b32_e32 v26, v217
	ds_read_b32 v27, v130
	ds_read_b32 v28, v131
	s_waitcnt lgkmcnt(0)
	v_max_f32_e64 v28, |v28|, |v28|
	s_waitcnt vmcnt(0)
	v_add_f32_e32 v26, v26, v27
	v_mul_f32_e32 v27, 0xbfb8aa3b, v26
	v_fma_f32 v29, v26, s42, -v27
	v_rndne_f32_e32 v30, v27
	v_fmac_f32_e32 v29, 0xb2a5705f, v26
	v_sub_f32_e32 v27, v27, v30
	v_add_f32_e32 v27, v27, v29
	v_cvt_i32_f32_e32 v30, v30
	v_exp_f32_e32 v27, v27
	v_cmp_nlt_f32_e32 vcc, s43, v26
	v_ldexp_f32 v27, v27, v30
	s_nop 0
	v_cndmask_b32_e32 v27, 0, v27, vcc
	v_cmp_ngt_f32_e32 vcc, s44, v26
	s_nop 1
	v_cndmask_b32_e32 v26, v209, v27, vcc
	v_max_f32_e32 v26, v28, v26
	v_div_scale_f32 v27, s[16:17], v26, v26, 1.0
	v_rcp_f32_e32 v28, v27
	v_div_scale_f32 v29, vcc, 1.0, v26, 1.0
	v_fma_f32 v30, -v27, v28, 1.0
	v_fmac_f32_e32 v28, v30, v28
	v_mul_f32_e32 v30, v29, v28
	v_fma_f32 v31, -v27, v30, v29
	v_fmac_f32_e32 v30, v31, v28
	v_fma_f32 v27, -v27, v30, v29
	v_div_fmas_f32 v27, v27, v28, v30
	v_div_fixup_f32 v26, v27, v26, 1.0
	v_mul_f32_e32 v31, v61, v26
	v_mul_f32_e32 v37, v57, v26
	v_mul_f32_e32 v26, v31, v31
	v_fmac_f32_e32 v26, v37, v37
	v_mov_b32_e32 v217, v26
	v_mov_b32_e32 v26, v218
	s_waitcnt lgkmcnt(0)
	ds_read_b32 v27, v134
	ds_read_b32 v28, v135
	s_waitcnt lgkmcnt(0)
	v_max_f32_e64 v28, |v28|, |v28|
	s_waitcnt vmcnt(0)
	v_add_f32_e32 v26, v26, v27
	v_mul_f32_e32 v27, 0xbfb8aa3b, v26
	v_fma_f32 v29, v26, s42, -v27
	v_rndne_f32_e32 v30, v27
	v_fmac_f32_e32 v29, 0xb2a5705f, v26
	v_sub_f32_e32 v27, v27, v30
	v_add_f32_e32 v27, v27, v29
	v_cvt_i32_f32_e32 v30, v30
	v_exp_f32_e32 v27, v27
	v_cmp_nlt_f32_e32 vcc, s43, v26
	v_ldexp_f32 v27, v27, v30
	s_nop 0
	v_cndmask_b32_e32 v27, 0, v27, vcc
	v_cmp_ngt_f32_e32 vcc, s44, v26
	s_nop 1
	v_cndmask_b32_e32 v26, v209, v27, vcc
	v_max_f32_e32 v26, v28, v26
	v_div_scale_f32 v27, s[16:17], v26, v26, 1.0
	v_rcp_f32_e32 v28, v27
	v_div_scale_f32 v29, vcc, 1.0, v26, 1.0
	v_fma_f32 v30, -v27, v28, 1.0
	v_fmac_f32_e32 v28, v30, v28
	v_mul_f32_e32 v30, v29, v28
	v_fma_f32 v33, -v27, v30, v29
	v_fmac_f32_e32 v30, v33, v28
	v_fma_f32 v27, -v27, v30, v29
	v_div_fmas_f32 v27, v27, v28, v30
	v_div_fixup_f32 v26, v27, v26, 1.0
	v_mul_f32_e32 v29, v62, v26
	v_mul_f32_e32 v36, v58, v26
	v_mul_f32_e32 v26, v29, v29
	v_fmac_f32_e32 v26, v36, v36
	v_mov_b32_e32 v218, v26
	v_mov_b32_e32 v26, v219
	s_waitcnt lgkmcnt(0)
	ds_read_b32 v27, v138
	ds_read_b32 v28, v139
	s_waitcnt lgkmcnt(0)
	v_max_f32_e64 v28, |v28|, |v28|
	s_waitcnt vmcnt(0)
	v_add_f32_e32 v26, v26, v27
	v_mul_f32_e32 v27, 0xbfb8aa3b, v26
	v_fma_f32 v30, v26, s42, -v27
	v_rndne_f32_e32 v33, v27
	v_fmac_f32_e32 v30, 0xb2a5705f, v26
	v_sub_f32_e32 v27, v27, v33
	v_add_f32_e32 v27, v27, v30
	v_cvt_i32_f32_e32 v33, v33
	v_exp_f32_e32 v27, v27
	v_cmp_nlt_f32_e32 vcc, s43, v26
	v_ldexp_f32 v27, v27, v33
	s_nop 0
	v_cndmask_b32_e32 v27, 0, v27, vcc
	v_cmp_ngt_f32_e32 vcc, s44, v26
	s_nop 1
	v_cndmask_b32_e32 v26, v209, v27, vcc
	v_max_f32_e32 v26, v28, v26
	v_div_scale_f32 v27, s[16:17], v26, v26, 1.0
	v_rcp_f32_e32 v28, v27
	v_div_scale_f32 v30, vcc, 1.0, v26, 1.0
	v_fma_f32 v33, -v27, v28, 1.0
	v_fmac_f32_e32 v28, v33, v28
	v_mul_f32_e32 v33, v30, v28
	v_fma_f32 v34, -v27, v33, v30
	v_fmac_f32_e32 v33, v34, v28
	v_fma_f32 v27, -v27, v33, v30
	v_div_fmas_f32 v27, v27, v28, v33
	v_div_fixup_f32 v26, v27, v26, 1.0
	v_mul_f32_e32 v27, v63, v26
	v_mul_f32_e32 v35, v59, v26
	v_mul_f32_e32 v26, v27, v27
	v_fmac_f32_e32 v26, v35, v35
	v_mov_b32_e32 v219, v26
	v_mov_b32_e32 v26, v220
	s_waitcnt lgkmcnt(0)
	ds_read_b32 v28, v142
	ds_read_b32 v30, v143
	s_waitcnt lgkmcnt(0)
	v_max_f32_e64 v30, |v30|, |v30|
	s_waitcnt vmcnt(0)
; __device__ __forceinline__ void lds_add(LAS float* p, float v) { __hip_atomic_fetch_add(p, v, __ATOMIC_RELAXED, __HIP_MEMORY_SCOPE_WORKGROUP); }
; __device__ __forceinline__ void mlstm_out_unit(const Frame& F, int c, int h, int tb) {
;     ...
; #pragma unroll
;     for (int tt = 0; tt < 4; ++tt)
; #pragma unroll
;         for (int j = 0; j < 4; ++j) { const int tl = tt * 16 + kg * 4 + j; const float mt = BC[t0 + tl] + sMr[tl]; const float dn = 1.f / fmaxf(fabsf(sDen[tl]), expf(-mt));
;             acc[tt][0][j] *= dn; acc[tt][1][j] *= dn; float q = acc[tt][0][j] * acc[tt][0][j] + acc[tt][1][j] * acc[tt][1][j];
;             q += __shfl_xor(q, 1); q += __shfl_xor(q, 2); q += __shfl_xor(q, 4); q += __shfl_xor(q, 8);
;             if (fr == 0) lds_add(&sSq[tl], q); }
	v_add_f32_e32 v26, v26, v28
	v_mul_f32_e32 v28, 0xbfb8aa3b, v26
	v_fma_f32 v33, v26, s42, -v28
	v_rndne_f32_e32 v34, v28
	v_fmac_f32_e32 v33, 0xb2a5705f, v26
	v_sub_f32_e32 v28, v28, v34
	v_add_f32_e32 v28, v28, v33
	v_cvt_i32_f32_e32 v34, v34
	v_exp_f32_e32 v28, v28
	v_cmp_nlt_f32_e32 vcc, s43, v26
	v_ldexp_f32 v28, v28, v34
	s_nop 0
	v_cndmask_b32_e32 v28, 0, v28, vcc
	v_cmp_ngt_f32_e32 vcc, s44, v26
	s_nop 1
	v_cndmask_b32_e32 v26, v209, v28, vcc
	v_max_f32_e32 v26, v30, v26
	v_div_scale_f32 v28, s[16:17], v26, v26, 1.0
	v_rcp_f32_e32 v30, v28
	v_div_scale_f32 v33, vcc, 1.0, v26, 1.0
	v_fma_f32 v34, -v28, v30, 1.0
	v_fmac_f32_e32 v30, v34, v30
	v_mul_f32_e32 v34, v33, v30
	v_fma_f32 v39, -v28, v34, v33
	v_fmac_f32_e32 v34, v39, v30
	v_fma_f32 v28, -v28, v34, v33
	v_div_fmas_f32 v28, v28, v30, v34
	v_div_fixup_f32 v26, v28, v26, 1.0
	v_mul_f32_e32 v34, v16, v26
	v_mul_f32_e32 v26, v20, v26
	v_mul_f32_e32 v16, v26, v26
	v_fmac_f32_e32 v16, v34, v34
	v_mov_b32_e32 v220, v16
	v_mov_b32_e32 v16, v221
	s_waitcnt lgkmcnt(0)
	ds_read_b32 v20, v151
	ds_read_b32 v28, v152
	s_waitcnt lgkmcnt(0)
	v_max_f32_e64 v28, |v28|, |v28|
	s_waitcnt vmcnt(0)
	v_add_f32_e32 v16, v16, v20
	v_mul_f32_e32 v20, 0xbfb8aa3b, v16
	v_fma_f32 v30, v16, s42, -v20
	v_rndne_f32_e32 v33, v20
	v_fmac_f32_e32 v30, 0xb2a5705f, v16
	v_sub_f32_e32 v20, v20, v33
	v_add_f32_e32 v20, v20, v30
	v_cvt_i32_f32_e32 v33, v33
	v_exp_f32_e32 v20, v20
	v_cmp_nlt_f32_e32 vcc, s43, v16
	v_ldexp_f32 v20, v20, v33
	s_nop 0
	v_cndmask_b32_e32 v20, 0, v20, vcc
	v_cmp_ngt_f32_e32 vcc, s44, v16
	s_nop 1
	v_cndmask_b32_e32 v16, v209, v20, vcc
	v_max_f32_e32 v16, v28, v16
	v_div_scale_f32 v20, s[16:17], v16, v16, 1.0
	v_rcp_f32_e32 v28, v20
	v_div_scale_f32 v30, vcc, 1.0, v16, 1.0
	v_fma_f32 v33, -v20, v28, 1.0
	v_fmac_f32_e32 v28, v33, v28
	v_mul_f32_e32 v33, v30, v28
	v_fma_f32 v39, -v20, v33, v30
	v_fmac_f32_e32 v33, v39, v28
	v_fma_f32 v20, -v20, v33, v30
	v_div_fmas_f32 v20, v20, v28, v33
	v_div_fixup_f32 v16, v20, v16, 1.0
	v_mul_f32_e32 v21, v21, v16
	v_mul_f32_e32 v33, v17, v16
	v_mul_f32_e32 v16, v21, v21
	v_fmac_f32_e32 v16, v33, v33
	v_mov_b32_e32 v221, v16
	v_mov_b32_e32 v16, v222
	s_waitcnt lgkmcnt(0)
	ds_read_b32 v17, v155
	ds_read_b32 v20, v156
	s_waitcnt lgkmcnt(0)
	v_max_f32_e64 v20, |v20|, |v20|
	s_waitcnt vmcnt(0)
	v_add_f32_e32 v16, v16, v17
	v_mul_f32_e32 v17, 0xbfb8aa3b, v16
	v_fma_f32 v28, v16, s42, -v17
	v_rndne_f32_e32 v30, v17
	v_fmac_f32_e32 v28, 0xb2a5705f, v16
	v_sub_f32_e32 v17, v17, v30
	v_add_f32_e32 v17, v17, v28
	v_cvt_i32_f32_e32 v30, v30
	v_exp_f32_e32 v17, v17
	v_cmp_nlt_f32_e32 vcc, s43, v16
	v_ldexp_f32 v17, v17, v30
	s_nop 0
	v_cndmask_b32_e32 v17, 0, v17, vcc
	v_cmp_ngt_f32_e32 vcc, s44, v16
	s_nop 1
	v_cndmask_b32_e32 v16, v209, v17, vcc
	v_max_f32_e32 v16, v20, v16
	v_div_scale_f32 v17, s[16:17], v16, v16, 1.0
	v_rcp_f32_e32 v20, v17
	v_div_scale_f32 v28, vcc, 1.0, v16, 1.0
	v_fma_f32 v30, -v17, v20, 1.0
	v_fmac_f32_e32 v20, v30, v20
	v_mul_f32_e32 v30, v28, v20
	v_fma_f32 v39, -v17, v30, v28
	v_fmac_f32_e32 v30, v39, v20
	v_fma_f32 v17, -v17, v30, v28
	v_div_fmas_f32 v17, v17, v20, v30
	v_div_fixup_f32 v16, v17, v16, 1.0
	v_mul_f32_e32 v20, v22, v16
	v_mul_f32_e32 v30, v18, v16
	v_mul_f32_e32 v16, v20, v20
	v_fmac_f32_e32 v16, v30, v30
	v_mov_b32_e32 v222, v16
	v_mov_b32_e32 v16, v223
	s_waitcnt lgkmcnt(0)
	ds_read_b32 v17, v159
	ds_read_b32 v18, v161
	s_waitcnt lgkmcnt(0)
	v_max_f32_e64 v18, |v18|, |v18|
	s_waitcnt vmcnt(0)
	v_add_f32_e32 v16, v16, v17
	v_mul_f32_e32 v17, 0xbfb8aa3b, v16
	v_fma_f32 v22, v16, s42, -v17
	v_rndne_f32_e32 v28, v17
	v_fmac_f32_e32 v22, 0xb2a5705f, v16
	v_sub_f32_e32 v17, v17, v28
	v_add_f32_e32 v17, v17, v22
	v_cvt_i32_f32_e32 v28, v28
	v_exp_f32_e32 v17, v17
	v_cmp_nlt_f32_e32 vcc, s43, v16
	v_ldexp_f32 v17, v17, v28
	s_nop 0
	v_cndmask_b32_e32 v17, 0, v17, vcc
	v_cmp_ngt_f32_e32 vcc, s44, v16
	s_nop 1
	v_cndmask_b32_e32 v16, v209, v17, vcc
	v_max_f32_e32 v16, v18, v16
	v_div_scale_f32 v17, s[16:17], v16, v16, 1.0
	v_rcp_f32_e32 v18, v17
	v_div_scale_f32 v22, vcc, 1.0, v16, 1.0
	v_fma_f32 v28, -v17, v18, 1.0
	v_fmac_f32_e32 v18, v28, v18
	v_mul_f32_e32 v28, v22, v18
	v_fma_f32 v39, -v17, v28, v22
	v_fmac_f32_e32 v28, v39, v18
	v_fma_f32 v17, -v17, v28, v22
	v_div_fmas_f32 v17, v17, v18, v28
	v_div_fixup_f32 v16, v17, v16, 1.0
	v_mul_f32_e32 v17, v23, v16
	v_mul_f32_e32 v28, v19, v16
	v_mul_f32_e32 v16, v17, v17
	v_fmac_f32_e32 v16, v28, v28
	v_mov_b32_e32 v223, v16
	v_mov_b32_e32 v16, v224
	s_waitcnt lgkmcnt(0)
	ds_read_b32 v18, v164
	ds_read_b32 v19, v165
	s_waitcnt lgkmcnt(0)
	v_max_f32_e64 v19, |v19|, |v19|
	s_waitcnt vmcnt(0)
	v_add_f32_e32 v16, v16, v18
	v_mul_f32_e32 v18, 0xbfb8aa3b, v16
	v_fma_f32 v22, v16, s42, -v18
	v_rndne_f32_e32 v23, v18
	v_fmac_f32_e32 v22, 0xb2a5705f, v16
	v_sub_f32_e32 v18, v18, v23
	v_add_f32_e32 v18, v18, v22
	v_cvt_i32_f32_e32 v23, v23
	v_exp_f32_e32 v18, v18
	v_cmp_nlt_f32_e32 vcc, s43, v16
	v_ldexp_f32 v18, v18, v23
	s_nop 0
	v_cndmask_b32_e32 v18, 0, v18, vcc
	v_cmp_ngt_f32_e32 vcc, s44, v16
	s_nop 1
	v_cndmask_b32_e32 v16, v209, v18, vcc
	v_max_f32_e32 v16, v19, v16
	v_div_scale_f32 v18, s[16:17], v16, v16, 1.0
	v_rcp_f32_e32 v19, v18
	v_div_scale_f32 v22, vcc, 1.0, v16, 1.0
	v_fma_f32 v23, -v18, v19, 1.0
	v_fmac_f32_e32 v19, v23, v19
	v_mul_f32_e32 v23, v22, v19
	v_fma_f32 v39, -v18, v23, v22
	v_fmac_f32_e32 v23, v39, v19
	v_fma_f32 v18, -v18, v23, v22
	v_div_fmas_f32 v18, v18, v19, v23
	v_div_fixup_f32 v16, v18, v16, 1.0
	v_mul_f32_e32 v23, v8, v16
	v_mul_f32_e32 v16, v12, v16
	v_mul_f32_e32 v8, v16, v16
	v_fmac_f32_e32 v8, v23, v23
	v_mov_b32_e32 v224, v8
	v_mov_b32_e32 v8, v225
	s_waitcnt lgkmcnt(0)
; __device__ __forceinline__ void lds_add(LAS float* p, float v) { __hip_atomic_fetch_add(p, v, __ATOMIC_RELAXED, __HIP_MEMORY_SCOPE_WORKGROUP); }
; __device__ __forceinline__ void mlstm_out_unit(const Frame& F, int c, int h, int tb) {
;     ...
; #pragma unroll
;     for (int tt = 0; tt < 4; ++tt)
; #pragma unroll
;         for (int j = 0; j < 4; ++j) { const int tl = tt * 16 + kg * 4 + j; const float mt = BC[t0 + tl] + sMr[tl]; const float dn = 1.f / fmaxf(fabsf(sDen[tl]), expf(-mt));
;             acc[tt][0][j] *= dn; acc[tt][1][j] *= dn; float q = acc[tt][0][j] * acc[tt][0][j] + acc[tt][1][j] * acc[tt][1][j];
;             q += __shfl_xor(q, 1); q += __shfl_xor(q, 2); q += __shfl_xor(q, 4); q += __shfl_xor(q, 8);
;             if (fr == 0) lds_add(&sSq[tl], q); }
	ds_read_b32 v12, v168
	ds_read_b32 v18, v169
	s_waitcnt lgkmcnt(0)
	v_max_f32_e64 v18, |v18|, |v18|
	s_waitcnt vmcnt(0)
	v_add_f32_e32 v8, v8, v12
	v_mul_f32_e32 v12, 0xbfb8aa3b, v8
	v_fma_f32 v19, v8, s42, -v12
	v_rndne_f32_e32 v22, v12
	v_fmac_f32_e32 v19, 0xb2a5705f, v8
	v_sub_f32_e32 v12, v12, v22
	v_add_f32_e32 v12, v12, v19
	v_cvt_i32_f32_e32 v22, v22
	v_exp_f32_e32 v12, v12
	v_cmp_nlt_f32_e32 vcc, s43, v8
	v_ldexp_f32 v12, v12, v22
	s_nop 0
	v_cndmask_b32_e32 v12, 0, v12, vcc
	v_cmp_ngt_f32_e32 vcc, s44, v8
	s_nop 1
	v_cndmask_b32_e32 v8, v209, v12, vcc
	v_max_f32_e32 v8, v18, v8
	v_div_scale_f32 v12, s[16:17], v8, v8, 1.0
	v_rcp_f32_e32 v18, v12
	v_div_scale_f32 v19, vcc, 1.0, v8, 1.0
	v_fma_f32 v22, -v12, v18, 1.0
	v_fmac_f32_e32 v18, v22, v18
	v_mul_f32_e32 v22, v19, v18
	v_fma_f32 v39, -v12, v22, v19
	v_fmac_f32_e32 v22, v39, v18
	v_fma_f32 v12, -v12, v22, v19
	v_div_fmas_f32 v12, v12, v18, v22
	v_div_fixup_f32 v8, v12, v8, 1.0
	v_mul_f32_e32 v13, v13, v8
	v_mul_f32_e32 v22, v9, v8
	v_mul_f32_e32 v8, v13, v13
	v_fmac_f32_e32 v8, v22, v22
	v_mov_b32_e32 v225, v8
	v_mov_b32_e32 v8, v226
	s_waitcnt lgkmcnt(0)
	ds_read_b32 v9, v172
	ds_read_b32 v12, v173
	s_waitcnt lgkmcnt(0)
	v_max_f32_e64 v12, |v12|, |v12|
	s_waitcnt vmcnt(0)
	v_add_f32_e32 v8, v8, v9
	v_mul_f32_e32 v9, 0xbfb8aa3b, v8
	v_fma_f32 v18, v8, s42, -v9
	v_rndne_f32_e32 v19, v9
	v_fmac_f32_e32 v18, 0xb2a5705f, v8
	v_sub_f32_e32 v9, v9, v19
	v_add_f32_e32 v9, v9, v18
	v_cvt_i32_f32_e32 v19, v19
	v_exp_f32_e32 v9, v9
	v_cmp_nlt_f32_e32 vcc, s43, v8
	v_ldexp_f32 v9, v9, v19
	s_nop 0
	v_cndmask_b32_e32 v9, 0, v9, vcc
	v_cmp_ngt_f32_e32 vcc, s44, v8
	s_nop 1
	v_cndmask_b32_e32 v8, v209, v9, vcc
	v_max_f32_e32 v8, v12, v8
	v_div_scale_f32 v9, s[16:17], v8, v8, 1.0
	v_rcp_f32_e32 v12, v9
	v_div_scale_f32 v18, vcc, 1.0, v8, 1.0
	v_fma_f32 v19, -v9, v12, 1.0
	v_fmac_f32_e32 v12, v19, v12
	v_mul_f32_e32 v19, v18, v12
	v_fma_f32 v39, -v9, v19, v18
	v_fmac_f32_e32 v19, v39, v12
	v_fma_f32 v9, -v9, v19, v18
	v_div_fmas_f32 v9, v9, v12, v19
	v_div_fixup_f32 v8, v9, v8, 1.0
	v_mul_f32_e32 v12, v14, v8
	v_mul_f32_e32 v19, v10, v8
	v_mul_f32_e32 v8, v12, v12
	v_fmac_f32_e32 v8, v19, v19
	v_mov_b32_e32 v226, v8
	v_mov_b32_e32 v8, v227
	s_waitcnt lgkmcnt(0)
	ds_read_b32 v9, v176
	ds_read_b32 v10, v177
	s_waitcnt lgkmcnt(0)
	v_max_f32_e64 v10, |v10|, |v10|
	s_waitcnt vmcnt(0)
	v_add_f32_e32 v8, v8, v9
	v_mul_f32_e32 v9, 0xbfb8aa3b, v8
	v_fma_f32 v14, v8, s42, -v9
	v_rndne_f32_e32 v18, v9
	v_fmac_f32_e32 v14, 0xb2a5705f, v8
	v_sub_f32_e32 v9, v9, v18
	v_add_f32_e32 v9, v9, v14
	v_cvt_i32_f32_e32 v18, v18
	v_exp_f32_e32 v9, v9
	v_cmp_nlt_f32_e32 vcc, s43, v8
	v_ldexp_f32 v9, v9, v18
	s_nop 0
	v_cndmask_b32_e32 v9, 0, v9, vcc
	v_cmp_ngt_f32_e32 vcc, s44, v8
	s_nop 1
	v_cndmask_b32_e32 v8, v209, v9, vcc
	v_max_f32_e32 v8, v10, v8
	v_div_scale_f32 v9, s[16:17], v8, v8, 1.0
	v_rcp_f32_e32 v10, v9
	v_div_scale_f32 v14, vcc, 1.0, v8, 1.0
	v_fma_f32 v18, -v9, v10, 1.0
	v_fmac_f32_e32 v10, v18, v10
	v_mul_f32_e32 v18, v14, v10
	v_fma_f32 v39, -v9, v18, v14
	v_fmac_f32_e32 v18, v39, v10
	v_fma_f32 v9, -v9, v18, v14
	v_div_fmas_f32 v9, v9, v10, v18
	v_div_fixup_f32 v8, v9, v8, 1.0
	v_mul_f32_e32 v10, v15, v8
	v_mul_f32_e32 v18, v11, v8
	v_mul_f32_e32 v8, v10, v10
	v_fmac_f32_e32 v8, v18, v18
	v_mov_b32_e32 v227, v8
	v_mov_b32_e32 v8, v228
	s_waitcnt lgkmcnt(0)
	ds_read_b32 v9, v180
	ds_read_b32 v11, v181
	s_waitcnt lgkmcnt(0)
	v_max_f32_e64 v11, |v11|, |v11|
	s_waitcnt vmcnt(0)
	v_add_f32_e32 v8, v8, v9
	v_mul_f32_e32 v9, 0xbfb8aa3b, v8
	v_fma_f32 v14, v8, s42, -v9
	v_rndne_f32_e32 v15, v9
	v_fmac_f32_e32 v14, 0xb2a5705f, v8
	v_sub_f32_e32 v9, v9, v15
	v_add_f32_e32 v9, v9, v14
	v_cvt_i32_f32_e32 v15, v15
	v_exp_f32_e32 v9, v9
	v_cmp_nlt_f32_e32 vcc, s43, v8
	v_ldexp_f32 v9, v9, v15
	s_nop 0
	v_cndmask_b32_e32 v9, 0, v9, vcc
	v_cmp_ngt_f32_e32 vcc, s44, v8
	s_nop 1
	v_cndmask_b32_e32 v8, v209, v9, vcc
	v_max_f32_e32 v8, v11, v8
	v_div_scale_f32 v9, s[16:17], v8, v8, 1.0
	v_rcp_f32_e32 v11, v9
	v_div_scale_f32 v14, vcc, 1.0, v8, 1.0
	v_fma_f32 v15, -v9, v11, 1.0
	v_fmac_f32_e32 v11, v15, v11
	v_mul_f32_e32 v15, v14, v11
	v_fma_f32 v39, -v9, v15, v14
	v_fmac_f32_e32 v15, v39, v11
	v_fma_f32 v9, -v9, v15, v14
	v_div_fmas_f32 v9, v9, v11, v15
	v_div_fixup_f32 v8, v9, v8, 1.0
	v_mul_f32_e32 v9, v4, v8
	v_mul_f32_e32 v15, v0, v8
	v_mul_f32_e32 v0, v9, v9
	v_fmac_f32_e32 v0, v15, v15
	v_mov_b32_e32 v228, v0
	v_mov_b32_e32 v0, v229
	s_waitcnt lgkmcnt(0)
	ds_read_b32 v4, v184
	ds_read_b32 v8, v185
	s_waitcnt lgkmcnt(0)
	v_max_f32_e64 v8, |v8|, |v8|
	s_waitcnt vmcnt(0)
	v_add_f32_e32 v0, v0, v4
	v_mul_f32_e32 v4, 0xbfb8aa3b, v0
	v_fma_f32 v11, v0, s42, -v4
	v_rndne_f32_e32 v14, v4
	v_fmac_f32_e32 v11, 0xb2a5705f, v0
	v_sub_f32_e32 v4, v4, v14
	v_add_f32_e32 v4, v4, v11
	v_cvt_i32_f32_e32 v14, v14
	v_exp_f32_e32 v4, v4
	v_cmp_nlt_f32_e32 vcc, s43, v0
	v_ldexp_f32 v4, v4, v14
	s_nop 0
	v_cndmask_b32_e32 v4, 0, v4, vcc
	v_cmp_ngt_f32_e32 vcc, s44, v0
	s_nop 1
	v_cndmask_b32_e32 v0, v209, v4, vcc
	v_max_f32_e32 v0, v8, v0
	v_div_scale_f32 v4, s[16:17], v0, v0, 1.0
	v_rcp_f32_e32 v8, v4
	v_div_scale_f32 v11, vcc, 1.0, v0, 1.0
	v_fma_f32 v14, -v4, v8, 1.0
	v_fmac_f32_e32 v8, v14, v8
	v_mul_f32_e32 v14, v11, v8
	v_fma_f32 v39, -v4, v14, v11
	v_fmac_f32_e32 v14, v39, v8
	v_fma_f32 v4, -v4, v14, v11
	v_div_fmas_f32 v4, v4, v8, v14
	v_div_fixup_f32 v0, v4, v0, 1.0
	v_mul_f32_e32 v8, v5, v0
	v_mul_f32_e32 v14, v1, v0
	v_mul_f32_e32 v0, v8, v8
	v_fmac_f32_e32 v0, v14, v14
	v_mov_b32_e32 v229, v0
	v_mov_b32_e32 v0, v230
	s_waitcnt lgkmcnt(0)
	ds_read_b32 v1, v188
	ds_read_b32 v4, v189
	s_waitcnt lgkmcnt(0)
; __device__ __forceinline__ void lds_add(LAS float* p, float v) { __hip_atomic_fetch_add(p, v, __ATOMIC_RELAXED, __HIP_MEMORY_SCOPE_WORKGROUP); }
; __device__ __forceinline__ void mlstm_out_unit(const Frame& F, int c, int h, int tb) {
;     ...
; #pragma unroll
;     for (int tt = 0; tt < 4; ++tt)
; #pragma unroll
;         for (int j = 0; j < 4; ++j) { const int tl = tt * 16 + kg * 4 + j; const float mt = BC[t0 + tl] + sMr[tl]; const float dn = 1.f / fmaxf(fabsf(sDen[tl]), expf(-mt));
;             acc[tt][0][j] *= dn; acc[tt][1][j] *= dn; float q = acc[tt][0][j] * acc[tt][0][j] + acc[tt][1][j] * acc[tt][1][j];
;             q += __shfl_xor(q, 1); q += __shfl_xor(q, 2); q += __shfl_xor(q, 4); q += __shfl_xor(q, 8);
;             if (fr == 0) lds_add(&sSq[tl], q); }
	v_max_f32_e64 v4, |v4|, |v4|
	s_waitcnt vmcnt(0)
	v_add_f32_e32 v0, v0, v1
	v_mul_f32_e32 v1, 0xbfb8aa3b, v0
	v_fma_f32 v5, v0, s42, -v1
	v_rndne_f32_e32 v11, v1
	v_fmac_f32_e32 v5, 0xb2a5705f, v0
	v_sub_f32_e32 v1, v1, v11
	v_add_f32_e32 v1, v1, v5
	v_cvt_i32_f32_e32 v11, v11
	v_exp_f32_e32 v1, v1
	v_cmp_nlt_f32_e32 vcc, s43, v0
	v_ldexp_f32 v1, v1, v11
	s_nop 0
	v_cndmask_b32_e32 v1, 0, v1, vcc
	v_cmp_ngt_f32_e32 vcc, s44, v0
	s_nop 1
	v_cndmask_b32_e32 v0, v209, v1, vcc
	v_max_f32_e32 v0, v4, v0
	v_div_scale_f32 v1, s[16:17], v0, v0, 1.0
	v_rcp_f32_e32 v4, v1
	v_div_scale_f32 v5, vcc, 1.0, v0, 1.0
	v_fma_f32 v11, -v1, v4, 1.0
	v_fmac_f32_e32 v4, v11, v4
	v_mul_f32_e32 v11, v5, v4
	v_fma_f32 v39, -v1, v11, v5
	v_fmac_f32_e32 v11, v39, v4
	v_fma_f32 v1, -v1, v11, v5
	v_div_fmas_f32 v1, v1, v4, v11
	v_div_fixup_f32 v0, v1, v0, 1.0
	v_mul_f32_e32 v5, v6, v0
	v_mul_f32_e32 v11, v2, v0
	v_mul_f32_e32 v0, v5, v5
	v_fmac_f32_e32 v0, v11, v11
	v_mov_b32_e32 v230, v0
	v_mov_b32_e32 v0, v231
	s_waitcnt lgkmcnt(0)
	ds_read_b32 v1, v192
	ds_read_b32 v2, v193
	s_waitcnt lgkmcnt(0)
	v_max_f32_e64 v2, |v2|, |v2|
	s_waitcnt vmcnt(0)
	v_add_f32_e32 v0, v0, v1
	v_mul_f32_e32 v1, 0xbfb8aa3b, v0
	v_fma_f32 v4, v0, s42, -v1
	v_rndne_f32_e32 v6, v1
	v_fmac_f32_e32 v4, 0xb2a5705f, v0
	v_sub_f32_e32 v1, v1, v6
	v_add_f32_e32 v1, v1, v4
	v_cvt_i32_f32_e32 v6, v6
	v_exp_f32_e32 v1, v1
	v_cmp_nlt_f32_e32 vcc, s43, v0
	v_ldexp_f32 v1, v1, v6
	s_nop 0
	v_cndmask_b32_e32 v1, 0, v1, vcc
	v_cmp_ngt_f32_e32 vcc, s44, v0
	s_nop 1
	v_cndmask_b32_e32 v0, v209, v1, vcc
	v_max_f32_e32 v0, v2, v0
	v_div_scale_f32 v1, s[16:17], v0, v0, 1.0
	v_rcp_f32_e32 v2, v1
	v_div_scale_f32 v4, vcc, 1.0, v0, 1.0
	v_fma_f32 v6, -v1, v2, 1.0
	v_fmac_f32_e32 v2, v6, v2
	v_mul_f32_e32 v6, v4, v2
	v_fma_f32 v24, -v1, v6, v4
	v_fmac_f32_e32 v6, v24, v2
	v_fma_f32 v1, -v1, v6, v4
	v_div_fmas_f32 v1, v1, v2, v6
	v_div_fixup_f32 v0, v1, v0, 1.0
	v_mul_f32_e32 v4, v7, v0
	v_mul_f32_e32 v6, v3, v0
	v_mul_f32_e32 v0, v4, v4
	v_fmac_f32_e32 v0, v6, v6
	v_mov_b32_e32 v231, v0
	ds_bpermute_b32 v232, v73, v216
	ds_bpermute_b32 v233, v73, v217
	ds_bpermute_b32 v234, v73, v218
	ds_bpermute_b32 v235, v73, v219
	ds_bpermute_b32 v236, v73, v220
	ds_bpermute_b32 v237, v73, v221
	ds_bpermute_b32 v238, v73, v222
	ds_bpermute_b32 v239, v73, v223
	s_waitcnt lgkmcnt(0)
	v_add_f32_e32 v216, v216, v232
	v_add_f32_e32 v217, v217, v233
	v_add_f32_e32 v218, v218, v234
	v_add_f32_e32 v219, v219, v235
	v_add_f32_e32 v220, v220, v236
	v_add_f32_e32 v221, v221, v237
	v_add_f32_e32 v222, v222, v238
	v_add_f32_e32 v223, v223, v239
	ds_bpermute_b32 v232, v92, v216
	ds_bpermute_b32 v233, v92, v217
	ds_bpermute_b32 v234, v92, v218
	ds_bpermute_b32 v235, v92, v219
	ds_bpermute_b32 v236, v92, v220
	ds_bpermute_b32 v237, v92, v221
	ds_bpermute_b32 v238, v92, v222
	ds_bpermute_b32 v239, v92, v223
	s_waitcnt lgkmcnt(0)
	v_add_f32_e32 v216, v216, v232
	v_add_f32_e32 v217, v217, v233
	v_add_f32_e32 v218, v218, v234
	v_add_f32_e32 v219, v219, v235
	v_add_f32_e32 v220, v220, v236
	v_add_f32_e32 v221, v221, v237
	v_add_f32_e32 v222, v222, v238
	v_add_f32_e32 v223, v223, v239
	ds_bpermute_b32 v232, v93, v216
	ds_bpermute_b32 v233, v93, v217
	ds_bpermute_b32 v234, v93, v218
	ds_bpermute_b32 v235, v93, v219
	ds_bpermute_b32 v236, v93, v220
	ds_bpermute_b32 v237, v93, v221
	ds_bpermute_b32 v238, v93, v222
	ds_bpermute_b32 v239, v93, v223
	s_waitcnt lgkmcnt(0)
	v_add_f32_e32 v216, v216, v232
	v_add_f32_e32 v217, v217, v233
	v_add_f32_e32 v218, v218, v234
	v_add_f32_e32 v219, v219, v235
	v_add_f32_e32 v220, v220, v236
	v_add_f32_e32 v221, v221, v237
	v_add_f32_e32 v222, v222, v238
	v_add_f32_e32 v223, v223, v239
	ds_bpermute_b32 v232, v94, v216
	ds_bpermute_b32 v233, v94, v217
	ds_bpermute_b32 v234, v94, v218
	ds_bpermute_b32 v235, v94, v219
	ds_bpermute_b32 v236, v94, v220
	ds_bpermute_b32 v237, v94, v221
	ds_bpermute_b32 v238, v94, v222
	ds_bpermute_b32 v239, v94, v223
	s_waitcnt lgkmcnt(0)
	v_add_f32_e32 v216, v216, v232
	v_add_f32_e32 v217, v217, v233
	v_add_f32_e32 v218, v218, v234
	v_add_f32_e32 v219, v219, v235
	v_add_f32_e32 v220, v220, v236
	v_add_f32_e32 v221, v221, v237
	v_add_f32_e32 v222, v222, v238
	v_add_f32_e32 v223, v223, v239
	ds_bpermute_b32 v232, v73, v224
	ds_bpermute_b32 v233, v73, v225
	ds_bpermute_b32 v234, v73, v226
	ds_bpermute_b32 v235, v73, v227
	ds_bpermute_b32 v236, v73, v228
	ds_bpermute_b32 v237, v73, v229
	ds_bpermute_b32 v238, v73, v230
	ds_bpermute_b32 v239, v73, v231
	s_waitcnt lgkmcnt(0)
	v_add_f32_e32 v224, v224, v232
	v_add_f32_e32 v225, v225, v233
	v_add_f32_e32 v226, v226, v234
	v_add_f32_e32 v227, v227, v235
	v_add_f32_e32 v228, v228, v236
	v_add_f32_e32 v229, v229, v237
	v_add_f32_e32 v230, v230, v238
	v_add_f32_e32 v231, v231, v239
	ds_bpermute_b32 v232, v92, v224
	ds_bpermute_b32 v233, v92, v225
	ds_bpermute_b32 v234, v92, v226
	ds_bpermute_b32 v235, v92, v227
	ds_bpermute_b32 v236, v92, v228
	ds_bpermute_b32 v237, v92, v229
	ds_bpermute_b32 v238, v92, v230
	ds_bpermute_b32 v239, v92, v231
	s_waitcnt lgkmcnt(0)
	v_add_f32_e32 v224, v224, v232
	v_add_f32_e32 v225, v225, v233
	v_add_f32_e32 v226, v226, v234
	v_add_f32_e32 v227, v227, v235
	v_add_f32_e32 v228, v228, v236
	v_add_f32_e32 v229, v229, v237
	v_add_f32_e32 v230, v230, v238
	v_add_f32_e32 v231, v231, v239
	ds_bpermute_b32 v232, v93, v224
	ds_bpermute_b32 v233, v93, v225
	ds_bpermute_b32 v234, v93, v226
	ds_bpermute_b32 v235, v93, v227
	ds_bpermute_b32 v236, v93, v228
	ds_bpermute_b32 v237, v93, v229
	ds_bpermute_b32 v238, v93, v230
	ds_bpermute_b32 v239, v93, v231
	s_waitcnt lgkmcnt(0)
	v_add_f32_e32 v224, v224, v232
	v_add_f32_e32 v225, v225, v233
	v_add_f32_e32 v226, v226, v234
	v_add_f32_e32 v227, v227, v235
	v_add_f32_e32 v228, v228, v236
	v_add_f32_e32 v229, v229, v237
	v_add_f32_e32 v230, v230, v238
	v_add_f32_e32 v231, v231, v239
	ds_bpermute_b32 v232, v94, v224
	ds_bpermute_b32 v233, v94, v225
	ds_bpermute_b32 v234, v94, v226
	ds_bpermute_b32 v235, v94, v227
	ds_bpermute_b32 v236, v94, v228
	ds_bpermute_b32 v237, v94, v229
	ds_bpermute_b32 v238, v94, v230
	ds_bpermute_b32 v239, v94, v231
	s_waitcnt lgkmcnt(0)
	v_add_f32_e32 v224, v224, v232
	v_add_f32_e32 v225, v225, v233
	v_add_f32_e32 v226, v226, v234
	v_add_f32_e32 v227, v227, v235
	v_add_f32_e32 v228, v228, v236
	v_add_f32_e32 v229, v229, v237
	v_add_f32_e32 v230, v230, v238
	v_add_f32_e32 v231, v231, v239
	s_and_saveexec_b64 s[16:17], s[4:5]
	ds_add_f32 v128, v216
	ds_add_f32 v132, v217
	ds_add_f32 v136, v218
	ds_add_f32 v140, v219
	ds_add_f32 v147, v220
	ds_add_f32 v153, v221
	ds_add_f32 v157, v222
	ds_add_f32 v162, v223
	ds_add_f32 v166, v224
	ds_add_f32 v170, v225
	ds_add_f32 v174, v226
	ds_add_f32 v178, v227
	ds_add_f32 v182, v228
	ds_add_f32 v186, v229
	ds_add_f32 v190, v230
	ds_add_f32 v194, v231
	s_branch .LBB0_738
